# store-GEMM epilogue mid-wait vmcnt(0)->vmcnt(15) (no longer drains next-tile prefetch + stores); cross-attention unit prologue vmcnt(0)->vmcnt(8)
# baseline (speedup 1.0000x reference)
; __device__ __forceinline__ unsigned cvtpk(float lo, float hi) { f32x2_t v = {lo, hi}; bf16x2_t b = __builtin_convertvector(v, bf16x2_t); return __builtin_bit_cast(unsigned, b); }
;     __device__ __forceinline__ void operator()(const f32x4 (&acc)[2][2][4][2], const Unit& u, int wr, int wc, int fr, int fq, const float (&pre)[8]) const {
;         const int row0 = u.pm * 256 + wr * 64 + fr, col0 = u.pn * 256 + wc * 32 + 8 * fq;
; #pragma unroll
;         for (int ai = 0; ai < 2; ++ai)
; #pragma unroll
;             for (int m = 0; m < 4; ++m) { bf16_t* rowp = O + (size_t)(row0 + ai * 128 + m * 16) * ldc + col0; const float r = RS ? rsqrtf(pre[ai * 4 + m] * (1.f / 1024.f) + 1e-6f) : 1.f;
; #pragma unroll
;                 for (int bj = 0; bj < 2; ++bj) { const f32x4 v0 = acc[ai][bj][m][0] * r, v1 = acc[ai][bj][m][1] * r; u32x4 w; w.x = cvtpk(v0[0], v0[1]); w.y = cvtpk(v0[2], v0[3]); w.z = cvtpk(v1[0], v1[1]); w.w = cvtpk(v1[2], v1[3]);
;                     *(u32x4*)(rowp + bj * 128) = w; } }
.LBB0_227:
	v_lshl_add_u32 v153, s93, 8, v145
	v_ashrrev_i32_e32 v141, 31, v153
	v_mul_lo_u32 v160, s68, v141
	v_mul_lo_u32 v141, s69, v153
	v_mad_u64_u32 v[156:157], s[14:15], s68, v153, 0
	s_waitcnt vmcnt(8)
	v_fmamk_f32 v140, v140, 0x3a800000, v189
	v_add3_u32 v157, v157, v160, v141
	v_mul_f32_e32 v141, 0x4b800000, v140
	v_cmp_gt_f32_e32 vcc, s27, v140
	v_lshl_or_b32 v154, s91, 8, v151
	v_ashrrev_i32_e32 v155, 31, v154
	v_cndmask_b32_e32 v140, v140, v141, vcc
	v_rsq_f32_e32 v158, v140
	v_lshl_add_u64 v[156:157], v[156:157], 1, s[62:63]
	v_lshlrev_b64 v[140:141], 1, v[154:155]
	v_lshl_add_u64 v[154:155], v[156:157], 0, v[140:141]
	v_mul_f32_e32 v156, 0x45800000, v158
	v_cndmask_b32_e32 v156, v158, v156, vcc
	v_cndmask_b32_e64 v156, v156, 1.0, s[70:71]
	v_pk_mul_f32 v[128:129], v[156:157], v[128:129] op_sel_hi:[0,1]
	v_pk_mul_f32 v[126:127], v[156:157], v[126:127] op_sel_hi:[0,1]
	v_pk_mul_f32 v[158:159], v[156:157], v[124:125] op_sel_hi:[0,1]
	v_pk_mul_f32 v[124:125], v[156:157], v[122:123] op_sel_hi:[0,1]
	v_cvt_pk_bf16_f32 v122, v126, v127
	v_cvt_pk_bf16_f32 v123, v128, v129
	v_cvt_pk_bf16_f32 v124, v124, v125
	v_cvt_pk_bf16_f32 v125, v158, v159
	global_store_dwordx4 v[154:155], v[122:125], off
	v_pk_mul_f32 v[120:121], v[156:157], v[120:121] op_sel_hi:[0,1]
	v_pk_mul_f32 v[118:119], v[156:157], v[118:119] op_sel_hi:[0,1]
	v_pk_mul_f32 v[122:123], v[156:157], v[116:117] op_sel_hi:[0,1]
	v_pk_mul_f32 v[116:117], v[156:157], v[114:115] op_sel_hi:[0,1]
	v_cvt_pk_bf16_f32 v114, v118, v119
	v_cvt_pk_bf16_f32 v115, v120, v121
	v_cvt_pk_bf16_f32 v116, v116, v117
	v_cvt_pk_bf16_f32 v117, v122, v123
	global_store_dwordx4 v[154:155], v[114:117], off offset:256
	s_mov_b64 s[30:31], -1
	s_nop 0
	v_fmamk_f32 v117, v150, 0x3a800000, v189
	v_mul_f32_e32 v118, 0x4b800000, v117
	v_cmp_gt_f32_e32 vcc, s27, v117
	v_or_b32_e32 v114, 16, v153
	v_mul_lo_u32 v116, s69, v114
	v_cndmask_b32_e32 v117, v117, v118, vcc
	v_rsq_f32_e32 v117, v117
	v_mad_u64_u32 v[114:115], s[14:15], s68, v114, 0
	v_add3_u32 v115, v115, v160, v116
	v_mul_f32_e32 v116, 0x45800000, v117
	v_cndmask_b32_e32 v116, v117, v116, vcc
	v_cndmask_b32_e64 v116, v116, 1.0, s[70:71]
	v_lshl_add_u64 v[114:115], v[114:115], 1, s[62:63]
	v_pk_mul_f32 v[112:113], v[116:117], v[112:113] op_sel_hi:[0,1]
	v_pk_mul_f32 v[110:111], v[116:117], v[110:111] op_sel_hi:[0,1]
	v_pk_mul_f32 v[118:119], v[116:117], v[108:109] op_sel_hi:[0,1]
	v_pk_mul_f32 v[108:109], v[116:117], v[106:107] op_sel_hi:[0,1]
	v_lshl_add_u64 v[114:115], v[114:115], 0, v[140:141]
	v_cvt_pk_bf16_f32 v106, v110, v111
	v_cvt_pk_bf16_f32 v107, v112, v113
	v_cvt_pk_bf16_f32 v108, v108, v109
	v_cvt_pk_bf16_f32 v109, v118, v119
	global_store_dwordx4 v[114:115], v[106:109], off
	v_pk_mul_f32 v[104:105], v[116:117], v[104:105] op_sel_hi:[0,1]
	v_pk_mul_f32 v[102:103], v[116:117], v[102:103] op_sel_hi:[0,1]
	v_pk_mul_f32 v[106:107], v[116:117], v[100:101] op_sel_hi:[0,1]
	v_pk_mul_f32 v[100:101], v[116:117], v[98:99] op_sel_hi:[0,1]
	v_cvt_pk_bf16_f32 v98, v102, v103
	v_cvt_pk_bf16_f32 v99, v104, v105
	v_cvt_pk_bf16_f32 v100, v100, v101
	v_cvt_pk_bf16_f32 v101, v106, v107
	global_store_dwordx4 v[114:115], v[98:101], off offset:256
	s_nop 1
	v_fmamk_f32 v101, v149, 0x3a800000, v189
	v_mul_f32_e32 v102, 0x4b800000, v101
	v_cmp_gt_f32_e32 vcc, s27, v101
	v_or_b32_e32 v98, 32, v153
	v_mul_lo_u32 v100, s69, v98
	v_cndmask_b32_e32 v101, v101, v102, vcc
	v_rsq_f32_e32 v101, v101
	v_mad_u64_u32 v[98:99], s[14:15], s68, v98, 0
	v_add3_u32 v99, v99, v160, v100
	v_mul_f32_e32 v100, 0x45800000, v101
	v_cndmask_b32_e32 v100, v101, v100, vcc
	v_cndmask_b32_e64 v100, v100, 1.0, s[70:71]
	v_lshl_add_u64 v[98:99], v[98:99], 1, s[62:63]
	v_pk_mul_f32 v[96:97], v[100:101], v[96:97] op_sel_hi:[0,1]
	v_pk_mul_f32 v[94:95], v[100:101], v[94:95] op_sel_hi:[0,1]
	v_pk_mul_f32 v[102:103], v[100:101], v[92:93] op_sel_hi:[0,1]
	v_pk_mul_f32 v[92:93], v[100:101], v[90:91] op_sel_hi:[0,1]
	v_lshl_add_u64 v[98:99], v[98:99], 0, v[140:141]
	v_cvt_pk_bf16_f32 v90, v94, v95
	v_cvt_pk_bf16_f32 v91, v96, v97
	v_cvt_pk_bf16_f32 v92, v92, v93
	v_cvt_pk_bf16_f32 v93, v102, v103
	global_store_dwordx4 v[98:99], v[90:93], off
	v_pk_mul_f32 v[88:89], v[100:101], v[88:89] op_sel_hi:[0,1]
	v_pk_mul_f32 v[86:87], v[100:101], v[86:87] op_sel_hi:[0,1]
	v_pk_mul_f32 v[90:91], v[100:101], v[84:85] op_sel_hi:[0,1]
	v_pk_mul_f32 v[84:85], v[100:101], v[82:83] op_sel_hi:[0,1]
	v_cvt_pk_bf16_f32 v82, v86, v87
	v_cvt_pk_bf16_f32 v83, v88, v89
	v_cvt_pk_bf16_f32 v84, v84, v85
	v_cvt_pk_bf16_f32 v85, v90, v91
	global_store_dwordx4 v[98:99], v[82:85], off offset:256
	s_nop 1
	v_fmamk_f32 v85, v148, 0x3a800000, v189
	v_mul_f32_e32 v86, 0x4b800000, v85
	v_cmp_gt_f32_e32 vcc, s27, v85
	v_or_b32_e32 v82, 48, v153
	v_mul_lo_u32 v84, s69, v82
	v_cndmask_b32_e32 v85, v85, v86, vcc
	v_rsq_f32_e32 v85, v85
	v_mad_u64_u32 v[82:83], s[14:15], s68, v82, 0
	v_add3_u32 v83, v83, v160, v84
	v_mul_f32_e32 v84, 0x45800000, v85
	v_cndmask_b32_e32 v84, v85, v84, vcc
	v_cndmask_b32_e64 v84, v84, 1.0, s[70:71]
	v_lshl_add_u64 v[82:83], v[82:83], 1, s[62:63]
	v_pk_mul_f32 v[80:81], v[84:85], v[80:81] op_sel_hi:[0,1]
	v_pk_mul_f32 v[78:79], v[84:85], v[78:79] op_sel_hi:[0,1]
	v_pk_mul_f32 v[86:87], v[84:85], v[76:77] op_sel_hi:[0,1]
	v_pk_mul_f32 v[76:77], v[84:85], v[74:75] op_sel_hi:[0,1]
	v_lshl_add_u64 v[82:83], v[82:83], 0, v[140:141]
	v_cvt_pk_bf16_f32 v74, v78, v79
	v_cvt_pk_bf16_f32 v75, v80, v81
	v_cvt_pk_bf16_f32 v76, v76, v77
	v_cvt_pk_bf16_f32 v77, v86, v87
	v_pk_mul_f32 v[70:71], v[84:85], v[70:71] op_sel_hi:[0,1]
	global_store_dwordx4 v[82:83], v[74:77], off
	v_pk_mul_f32 v[72:73], v[84:85], v[72:73] op_sel_hi:[0,1]
	s_nop 0
	v_pk_mul_f32 v[74:75], v[84:85], v[68:69] op_sel_hi:[0,1]
	v_pk_mul_f32 v[68:69], v[84:85], v[66:67] op_sel_hi:[0,1]
	v_cvt_pk_bf16_f32 v66, v70, v71
	s_waitcnt vmcnt(15)
; __device__ __forceinline__ unsigned cvtpk(float lo, float hi) { f32x2_t v = {lo, hi}; bf16x2_t b = __builtin_convertvector(v, bf16x2_t); return __builtin_bit_cast(unsigned, b); }
;     __device__ __forceinline__ void prefetch(const Unit& u, int wr, int fr, float (&pre)[8]) const {
;         const int row0 = u.pm * 256 + wr * 64 + fr;
; #pragma unroll
;         for (int i = 0; i < 8; ++i) pre[i] = RS ? RS[row0 + (i >> 2) * 128 + (i & 3) * 16] : 0.f;
;     }
;     __device__ __forceinline__ void operator()(const f32x4 (&acc)[2][2][4][2], const Unit& u, int wr, int wc, int fr, int fq, const float (&pre)[8]) const {
;         const int row0 = u.pm * 256 + wr * 64 + fr, col0 = u.pn * 256 + wc * 32 + 8 * fq;
; #pragma unroll
;         for (int ai = 0; ai < 2; ++ai)
; #pragma unroll
;             for (int m = 0; m < 4; ++m) { bf16_t* rowp = O + (size_t)(row0 + ai * 128 + m * 16) * ldc + col0; const float r = RS ? rsqrtf(pre[ai * 4 + m] * (1.f / 1024.f) + 1e-6f) : 1.f;
; #pragma unroll
;                 for (int bj = 0; bj < 2; ++bj) { const f32x4 v0 = acc[ai][bj][m][0] * r, v1 = acc[ai][bj][m][1] * r; u32x4 w; w.x = cvtpk(v0[0], v0[1]); w.y = cvtpk(v0[2], v0[3]); w.z = cvtpk(v1[0], v1[1]); w.w = cvtpk(v1[2], v1[3]);
;                     *(u32x4*)(rowp + bj * 128) = w; } }
	v_fmamk_f32 v70, v146, 0x3a800000, v189
	v_mul_f32_e32 v71, 0x4b800000, v70
	v_cmp_gt_f32_e32 vcc, s27, v70
	v_cvt_pk_bf16_f32 v67, v72, v73
	v_cvt_pk_bf16_f32 v68, v68, v69
	v_cndmask_b32_e32 v70, v70, v71, vcc
	v_cvt_pk_bf16_f32 v69, v74, v75
	v_rsq_f32_e32 v70, v70
	global_store_dwordx4 v[82:83], v[66:69], off offset:256
	s_nop 1
	v_add_u32_e32 v66, 0x80, v153
	v_ashrrev_i32_e32 v67, 31, v66
	v_mul_lo_u32 v68, s68, v67
	v_mul_lo_u32 v69, s69, v66
	v_mad_u64_u32 v[66:67], s[14:15], s68, v66, 0
	v_add3_u32 v67, v67, v68, v69
	v_mul_f32_e32 v68, 0x45800000, v70
	v_cndmask_b32_e32 v68, v70, v68, vcc
	v_cndmask_b32_e64 v68, v68, 1.0, s[70:71]
	v_lshl_add_u64 v[66:67], v[66:67], 1, s[62:63]
	v_pk_mul_f32 v[64:65], v[68:69], v[64:65] op_sel_hi:[0,1]
	v_pk_mul_f32 v[62:63], v[68:69], v[62:63] op_sel_hi:[0,1]
	v_pk_mul_f32 v[70:71], v[68:69], v[60:61] op_sel_hi:[0,1]
	v_pk_mul_f32 v[60:61], v[68:69], v[58:59] op_sel_hi:[0,1]
	v_lshl_add_u64 v[66:67], v[66:67], 0, v[140:141]
	v_cvt_pk_bf16_f32 v58, v62, v63
	v_cvt_pk_bf16_f32 v59, v64, v65
	v_cvt_pk_bf16_f32 v60, v60, v61
	v_cvt_pk_bf16_f32 v61, v70, v71
	v_pk_mul_f32 v[54:55], v[68:69], v[54:55] op_sel_hi:[0,1]
	global_store_dwordx4 v[66:67], v[58:61], off
	v_pk_mul_f32 v[56:57], v[68:69], v[56:57] op_sel_hi:[0,1]
	s_nop 0
	v_pk_mul_f32 v[58:59], v[68:69], v[52:53] op_sel_hi:[0,1]
	v_pk_mul_f32 v[52:53], v[68:69], v[50:51] op_sel_hi:[0,1]
	v_cvt_pk_bf16_f32 v50, v54, v55
	v_fmamk_f32 v54, v144, 0x3a800000, v189
	v_mul_f32_e32 v55, 0x4b800000, v54
	v_cmp_gt_f32_e32 vcc, s27, v54
	v_cvt_pk_bf16_f32 v51, v56, v57
	v_cvt_pk_bf16_f32 v52, v52, v53
	v_cndmask_b32_e32 v54, v54, v55, vcc
	v_cvt_pk_bf16_f32 v53, v58, v59
	v_rsq_f32_e32 v54, v54
	global_store_dwordx4 v[66:67], v[50:53], off offset:256
	s_nop 1
	v_add_u32_e32 v50, 0x90, v153
	v_ashrrev_i32_e32 v51, 31, v50
	v_mul_lo_u32 v52, s68, v51
	v_mul_lo_u32 v53, s69, v50
	v_mad_u64_u32 v[50:51], s[14:15], s68, v50, 0
	v_add3_u32 v51, v51, v52, v53
	v_mul_f32_e32 v52, 0x45800000, v54
	v_cndmask_b32_e32 v52, v54, v52, vcc
	v_cndmask_b32_e64 v52, v52, 1.0, s[70:71]
	v_lshl_add_u64 v[50:51], v[50:51], 1, s[62:63]
	v_pk_mul_f32 v[48:49], v[52:53], v[48:49] op_sel_hi:[0,1]
	v_pk_mul_f32 v[46:47], v[52:53], v[46:47] op_sel_hi:[0,1]
	v_pk_mul_f32 v[54:55], v[52:53], v[44:45] op_sel_hi:[0,1]
	v_pk_mul_f32 v[44:45], v[52:53], v[42:43] op_sel_hi:[0,1]
	v_lshl_add_u64 v[50:51], v[50:51], 0, v[140:141]
	v_cvt_pk_bf16_f32 v42, v46, v47
	v_cvt_pk_bf16_f32 v43, v48, v49
	v_cvt_pk_bf16_f32 v44, v44, v45
	v_cvt_pk_bf16_f32 v45, v54, v55
	v_pk_mul_f32 v[38:39], v[52:53], v[38:39] op_sel_hi:[0,1]
	global_store_dwordx4 v[50:51], v[42:45], off
	v_pk_mul_f32 v[40:41], v[52:53], v[40:41] op_sel_hi:[0,1]
	s_nop 0
	v_pk_mul_f32 v[42:43], v[52:53], v[36:37] op_sel_hi:[0,1]
	v_pk_mul_f32 v[36:37], v[52:53], v[34:35] op_sel_hi:[0,1]
	v_cvt_pk_bf16_f32 v34, v38, v39
	v_fmamk_f32 v38, v143, 0x3a800000, v189
	v_mul_f32_e32 v39, 0x4b800000, v38
	v_cmp_gt_f32_e32 vcc, s27, v38
	v_cvt_pk_bf16_f32 v35, v40, v41
	v_cvt_pk_bf16_f32 v36, v36, v37
	v_cndmask_b32_e32 v38, v38, v39, vcc
	v_cvt_pk_bf16_f32 v37, v42, v43
	v_rsq_f32_e32 v38, v38
	global_store_dwordx4 v[50:51], v[34:37], off offset:256
	s_nop 1
	v_add_u32_e32 v34, 0xa0, v153
	v_ashrrev_i32_e32 v35, 31, v34
	v_mul_lo_u32 v36, s68, v35
	v_mul_lo_u32 v37, s69, v34
	v_mad_u64_u32 v[34:35], s[14:15], s68, v34, 0
	v_add3_u32 v35, v35, v36, v37
	v_mul_f32_e32 v36, 0x45800000, v38
	v_cndmask_b32_e32 v36, v38, v36, vcc
	v_cndmask_b32_e64 v36, v36, 1.0, s[70:71]
	v_lshl_add_u64 v[34:35], v[34:35], 1, s[62:63]
	v_pk_mul_f32 v[32:33], v[36:37], v[32:33] op_sel_hi:[0,1]
	v_pk_mul_f32 v[30:31], v[36:37], v[30:31] op_sel_hi:[0,1]
	v_pk_mul_f32 v[38:39], v[36:37], v[28:29] op_sel_hi:[0,1]
	v_pk_mul_f32 v[28:29], v[36:37], v[26:27] op_sel_hi:[0,1]
	v_lshl_add_u64 v[34:35], v[34:35], 0, v[140:141]
	v_cvt_pk_bf16_f32 v26, v30, v31
	v_cvt_pk_bf16_f32 v27, v32, v33
	v_cvt_pk_bf16_f32 v28, v28, v29
	v_cvt_pk_bf16_f32 v29, v38, v39
	v_pk_mul_f32 v[22:23], v[36:37], v[22:23] op_sel_hi:[0,1]
	global_store_dwordx4 v[34:35], v[26:29], off
	v_pk_mul_f32 v[24:25], v[36:37], v[24:25] op_sel_hi:[0,1]
	s_nop 0
	v_pk_mul_f32 v[26:27], v[36:37], v[20:21] op_sel_hi:[0,1]
	v_pk_mul_f32 v[20:21], v[36:37], v[18:19] op_sel_hi:[0,1]
	v_cvt_pk_bf16_f32 v18, v22, v23
	v_fmamk_f32 v22, v142, 0x3a800000, v189
	v_mul_f32_e32 v23, 0x4b800000, v22
	v_cmp_gt_f32_e32 vcc, s27, v22
	v_cvt_pk_bf16_f32 v19, v24, v25
	v_cvt_pk_bf16_f32 v20, v20, v21
	v_cndmask_b32_e32 v22, v22, v23, vcc
	v_rsq_f32_e32 v22, v22
	v_cvt_pk_bf16_f32 v21, v26, v27
	global_store_dwordx4 v[34:35], v[18:21], off offset:256
	s_nop 1
	v_add_u32_e32 v19, 0xb0, v153
	v_mul_f32_e32 v18, 0x45800000, v22
	v_ashrrev_i32_e32 v20, 31, v19
	v_cndmask_b32_e32 v18, v22, v18, vcc
	v_mul_lo_u32 v22, s68, v20
	v_mul_lo_u32 v23, s69, v19
	v_mad_u64_u32 v[20:21], s[14:15], s68, v19, 0
	v_cndmask_b32_e64 v18, v18, 1.0, s[70:71]
	v_add3_u32 v21, v21, v22, v23
	v_lshl_add_u64 v[20:21], v[20:21], 1, s[62:63]
	v_pk_mul_f32 v[16:17], v[18:19], v[16:17] op_sel_hi:[0,1]
	v_pk_mul_f32 v[14:15], v[18:19], v[14:15] op_sel_hi:[0,1]
	v_pk_mul_f32 v[22:23], v[18:19], v[12:13] op_sel_hi:[0,1]
	v_pk_mul_f32 v[12:13], v[18:19], v[10:11] op_sel_hi:[0,1]
	v_lshl_add_u64 v[20:21], v[20:21], 0, v[140:141]
	v_cvt_pk_bf16_f32 v10, v14, v15
	v_cvt_pk_bf16_f32 v11, v16, v17
	v_cvt_pk_bf16_f32 v12, v12, v13
	v_cvt_pk_bf16_f32 v13, v22, v23
	global_store_dwordx4 v[20:21], v[10:13], off
	v_pk_mul_f32 v[8:9], v[18:19], v[8:9] op_sel_hi:[0,1]
	v_pk_mul_f32 v[6:7], v[18:19], v[6:7] op_sel_hi:[0,1]
	v_pk_mul_f32 v[10:11], v[18:19], v[4:5] op_sel_hi:[0,1]
	v_pk_mul_f32 v[4:5], v[18:19], v[2:3] op_sel_hi:[0,1]
	v_cvt_pk_bf16_f32 v2, v6, v7
	v_cvt_pk_bf16_f32 v3, v8, v9
	v_cvt_pk_bf16_f32 v4, v4, v5
	v_cvt_pk_bf16_f32 v5, v10, v11
	s_and_b64 vcc, exec, s[38:39]
	global_store_dwordx4 v[20:21], v[2:5], off offset:256
	s_cbranch_vccnz .LBB0_212
	s_nop 0
	v_lshl_add_u32 v2, s95, 8, v145
	v_mov_b32_e32 v149, 0
	s_and_b64 vcc, exec, s[36:37]
	v_ashrrev_i32_e32 v3, 31, v2
	v_mov_b32_e32 v140, 0
	v_mov_b32_e32 v150, 0
	s_cbranch_vccnz .LBB0_230
	v_lshl_add_u64 v[4:5], v[2:3], 2, s[66:67]
	global_load_dword v140, v[4:5], off
	global_load_dword v150, v[4:5], off offset:64

; template <bool DIFF> ...
;     ...
;     __syncthreads();
; __device__ __forceinline__ void run_phase(const Params& p, LAS unsigned char* lds, int ph, bool dummy) {
;     ...
;             for (int hh = 0; hh < 2; ++hh) { const int row = u.pm * 256 + hh * 128, b_ = row / SEQ, h = u.pn; const size_t qo = (size_t)row * DM + h * 256;
;                 const bf16_t* kp = kvl + (size_t)(b_ * MEML) * 2048 + h * 256;
;                 attn_unit<false>(lds, BIG + qo, DM, kp, kp + 1024, 2048, 4, 0, 0.0625f * LOG2E, 0.f, 0.f, OXA + qo, DM, nullptr, 1.f); } }
.LBB0_251:
	s_or_b32 s14, s14, s37
	s_ashr_i32 s15, s14, 31
	s_xor_b64 s[10:11], s[16:17], -1
	s_lshr_b32 s16, s15, 20
	s_add_i32 s16, s14, s16
	s_ashr_i32 s16, s16, 12
	s_lshl_b64 s[14:15], s[14:15], 10
	s_add_u32 s14, s14, s0
	s_addc_u32 s15, s15, s1
	s_lshl_b32 s16, s16, 8
	s_ashr_i32 s17, s16, 31
	s_lshl_b64 s[16:17], s[16:17], 12
	s_add_u32 s18, s38, s16
	v_mov_b32_e32 v56, v187
	s_addc_u32 s19, s39, s17
	s_lshl_b64 s[16:17], s[14:15], 1
	v_readlane_b32 s14, v252, 20
	v_readlane_b32 s15, v252, 21
	s_waitcnt vmcnt(8)
	v_add_u32_e32 v4, 0x200, v56
	s_add_u32 s14, s14, s16
	v_and_b32_e32 v57, 31, v56
	v_ashrrev_i32_e32 v34, 5, v56
	v_ashrrev_i32_e32 v36, 5, v4
	s_addc_u32 s15, s15, s17
	v_lshlrev_b32_e32 v0, 4, v57
	v_ashrrev_i32_e32 v35, 31, v34
	v_ashrrev_i32_e32 v37, 31, v36
	v_add_u32_e32 v10, 0x400, v56
	v_add_u32_e32 v12, 0x600, v56
	v_lshl_add_u64 v[30:31], s[14:15], 0, v[0:1]
	v_lshlrev_b64 v[2:3], 11, v[34:35]
	v_lshlrev_b64 v[4:5], 11, v[36:37]
	v_ashrrev_i32_e32 v38, 5, v10
	v_ashrrev_i32_e32 v40, 5, v12
	v_lshl_add_u64 v[2:3], v[30:31], 0, v[2:3]
	v_lshl_add_u64 v[6:7], v[30:31], 0, v[4:5]
	v_ashrrev_i32_e32 v39, 31, v38
	v_ashrrev_i32_e32 v41, 31, v40
	v_add_u32_e32 v18, 0x800, v56
	v_add_u32_e32 v20, 0xa00, v56
	s_barrier
; #define LAS __attribute__((address_space(3)))
; #define ATT_GLOAD(kt) do { _Pragma("unroll") for (int i = 0; i < NCH; ++i) { const size_t go = goff + (size_t)((kt) * 64 + i * (512 / CPR)) * kvpitch; \
;         kreg[i] = *(const u32x4*)(Kp + go); vreg[i] = *(const u32x4*)(Vp + go); } } while (0)
; template <bool DIFF> ...
;     ...
;     const int srow = tid / CPR, sch = tid % CPR;
;     const size_t goff = (size_t)srow * kvpitch + sch * 8;
;     const int loffk = srow * KSTR + sch * 16, loffv = KBY + srow * VSTR + sch * 16;
;     ...
;     constexpr int DSTG = 32768;
;     const int dch = (lane & 15) ^ ((((lane >> 4) & 3) << 2) | (wid & 3));
;     ...
;     __syncthreads();
;     if (DIFF) { ATT_DMA(nkt - 1, 0); }
;     else { ATT_GLOAD(0);
; #pragma unroll
;         for (int i = 0; i < 8; ++i) { const int id = tid + 512 * i, row = id >> 5, ch = id & 31;
;             *(LAS u32x4*)(lds + QOFF + row * QSTR + ch * 16) = *(const u32x4*)(Qp + (size_t)row * qpitch + ch * 8); }
;     }
;     const int wrow = qpos0 + qr;
;     f32x16 biasv;
;     { const float beta = DIFF ? sl2 / sc2 : 0.f;
; #pragma unroll
;       for (int r = 0; r < 16; ++r) biasv[r] = beta * (float)((r >> 2) * 8 + (r & 3) + hi * 4 - l32); }
	global_load_dwordx4 v[2:5], v[2:3], off
	s_nop 0
	global_load_dwordx4 v[6:9], v[6:7], off
	v_lshlrev_b64 v[10:11], 11, v[38:39]
	v_lshlrev_b64 v[12:13], 11, v[40:41]
	v_ashrrev_i32_e32 v42, 5, v18
	v_ashrrev_i32_e32 v44, 5, v20
	v_add_u32_e32 v26, 0xc00, v56
	v_lshl_add_u64 v[10:11], v[30:31], 0, v[10:11]
	v_lshl_add_u64 v[14:15], v[30:31], 0, v[12:13]
	v_ashrrev_i32_e32 v43, 31, v42
	v_ashrrev_i32_e32 v45, 31, v44
	v_ashrrev_i32_e32 v46, 5, v26
	global_load_dwordx4 v[10:13], v[10:11], off
	s_nop 0
	global_load_dwordx4 v[14:17], v[14:15], off
	v_lshlrev_b64 v[18:19], 11, v[42:43]
	v_lshlrev_b64 v[20:21], 11, v[44:45]
	v_ashrrev_i32_e32 v47, 31, v46
	v_lshl_add_u64 v[18:19], v[30:31], 0, v[18:19]
	v_lshl_add_u64 v[22:23], v[30:31], 0, v[20:21]
	v_lshlrev_b64 v[26:27], 11, v[46:47]
	global_load_dwordx4 v[18:21], v[18:19], off
	s_nop 0
	global_load_dwordx4 v[22:25], v[22:23], off
	v_lshl_add_u64 v[26:27], v[30:31], 0, v[26:27]
	global_load_dwordx4 v[26:29], v[26:27], off
	v_ashrrev_i32_e32 v35, 31, v56
	v_lshrrev_b32_e32 v35, 27, v35
	v_add_u32_e32 v32, 0xe00, v56
	v_add_u32_e32 v35, v56, v35
	v_ashrrev_i32_e32 v48, 5, v32
	v_ashrrev_i32_e32 v50, 5, v35
	v_and_b32_e32 v35, 0xffffffe0, v35
	v_ashrrev_i32_e32 v49, 31, v48
	v_sub_u32_e32 v35, v56, v35
	v_lshlrev_b64 v[32:33], 11, v[48:49]
	v_ashrrev_i32_e32 v51, 31, v50
	v_lshlrev_b32_e32 v54, 3, v35
	v_lshl_add_u64 v[30:31], v[30:31], 0, v[32:33]
	v_lshlrev_b64 v[52:53], 11, v[50:51]
	v_ashrrev_i32_e32 v55, 31, v54
	global_load_dwordx4 v[30:33], v[30:31], off
	v_lshl_add_u64 v[52:53], v[52:53], 0, v[54:55]
	v_lshl_add_u64 v[182:183], v[52:53], 1, s[18:19]
	v_add_co_u32_e32 v52, vcc, s26, v182
	global_load_dwordx4 v[114:117], v[182:183], off
	global_load_dwordx4 v[118:121], v[182:183], off offset:2048
	v_addc_co_u32_e32 v53, vcc, 0, v183, vcc
	global_load_dwordx4 v[122:125], v[52:53], off
	global_load_dwordx4 v[126:129], v[52:53], off offset:2048
	v_add_co_u32_e32 v52, vcc, s42, v182
	s_mov_b64 s[18:19], 0x800
	s_nop 0
	v_addc_co_u32_e32 v53, vcc, 0, v183, vcc
	global_load_dwordx4 v[130:133], v[52:53], off
	global_load_dwordx4 v[134:137], v[52:53], off offset:2048
	v_add_co_u32_e32 v52, vcc, s65, v182
	v_add_u32_e32 v0, s21, v0
	s_nop 0
	v_addc_co_u32_e32 v53, vcc, 0, v183, vcc
	global_load_dwordx4 v[138:141], v[52:53], off
	global_load_dwordx4 v[142:145], v[52:53], off offset:2048
	v_lshlrev_b32_e32 v198, 4, v35
	v_lshl_add_u64 v[184:185], v[182:183], 0, s[18:19]
	v_mad_u64_u32 v[34:35], s[18:19], v34, s4, v[0:1]
	v_mul_lo_u32 v37, v50, s4
	v_readfirstlane_b32 s14, v56
	v_add_u32_e32 v186, 0, v37
	s_lshr_b32 s15, s14, 1
	s_and_b32 s15, s15, 0x60
	v_or_b32_e32 v199, s15, v57
	s_and_b32 s15, s14, 0xffffff00
	s_add_i32 s15, s15, 0
	v_mad_u32_u24 v201, v57, s4, 0
	v_mad_u32_u24 v206, v199, s4, 0
	v_mov_b32_e32 v208, 0xff800000
	v_mov_b32_e32 v203, 0
	s_waitcnt vmcnt(15)
	ds_write_b128 v34, v[2:5]
	v_mad_u64_u32 v[2:3], s[18:19], v36, s4, v[0:1]
	s_waitcnt vmcnt(14)
	ds_write_b128 v2, v[6:9]
	v_mad_u64_u32 v[2:3], s[18:19], v38, s4, v[0:1]
	s_waitcnt vmcnt(13)
	ds_write_b128 v2, v[10:13]
	v_mad_u64_u32 v[2:3], s[18:19], v40, s4, v[0:1]
	s_waitcnt vmcnt(12)
	ds_write_b128 v2, v[14:17]
	v_mad_u64_u32 v[2:3], s[18:19], v42, s4, v[0:1]
	s_waitcnt vmcnt(11)
	ds_write_b128 v2, v[18:21]
	v_mad_u64_u32 v[2:3], s[18:19], v44, s4, v[0:1]
	v_bfe_u32 v18, v56, 5, 1
	s_waitcnt vmcnt(10)
	ds_write_b128 v2, v[22:25]
	v_mad_u64_u32 v[2:3], s[18:19], v46, s4, v[0:1]
	v_lshlrev_b32_e32 v197, 2, v18
	s_waitcnt vmcnt(9)
	ds_write_b128 v2, v[26:29]
	v_mad_u64_u32 v[2:3], s[18:19], v48, s4, v[0:1]
	v_sub_u32_e32 v0, v197, v57
	v_add_u32_e32 v16, 26, v0
	v_cvt_f32_i32_e32 v16, v16
	v_add_u32_e32 v14, 24, v0
	v_add_u32_e32 v15, 27, v0
	v_lshlrev_b32_e32 v200, 4, v18
	v_bfi_b32 v80, s33, 0, v16
	v_mad_u64_u32 v[16:17], s[18:19], v50, 48, v[186:187]
	v_lshrrev_b32_e32 v17, 2, v56
	v_and_b32_e32 v18, 16, v56
	v_lshlrev_b32_e32 v19, 2, v56
	s_waitcnt vmcnt(8)
	ds_write_b128 v2, v[30:33]
	v_add_u32_e32 v2, 1, v0
	v_add_u32_e32 v3, 3, v0
	v_add_u32_e32 v4, 2, v0
	v_add_u32_e32 v5, 9, v0
	v_add_u32_e32 v6, 8, v0
	v_add_u32_e32 v7, 11, v0
	v_add_u32_e32 v8, 10, v0
	v_add_u32_e32 v9, 17, v0
	v_add_u32_e32 v10, 16, v0
	v_add_u32_e32 v11, 19, v0
	v_add_u32_e32 v12, 18, v0
	v_add_u32_e32 v13, 25, v0
	v_cvt_f32_i32_e32 v14, v14
	v_cvt_f32_i32_e32 v15, v15
	v_and_or_b32 v17, v17, 3, v197
	v_and_or_b32 v18, v19, 12, v18
	v_cvt_f32_i32_e32 v2, v2
	v_cvt_f32_i32_e32 v4, v4
	v_cvt_f32_i32_e32 v3, v3
	v_cvt_f32_i32_e32 v6, v6
	v_cvt_f32_i32_e32 v5, v5
	v_cvt_f32_i32_e32 v8, v8
	v_cvt_f32_i32_e32 v7, v7
	v_cvt_f32_i32_e32 v10, v10
	v_cvt_f32_i32_e32 v9, v9
	v_cvt_f32_i32_e32 v12, v12
	v_cvt_f32_i32_e32 v11, v11
	v_cvt_f32_i32_e32 v0, v0
	v_cvt_f32_i32_e32 v13, v13
	v_mul_u32_u24_e32 v17, 0x240, v17
	v_lshlrev_b32_e32 v18, 1, v18
	v_add3_u32 v204, s15, v17, v18
	v_and_b32_e32 v18, 64, v190
	v_xor_b32_e32 v17, 32, v190
	v_add_u32_e32 v18, 64, v18
	v_bfi_b32 v81, s33, 0, v15
	v_bfi_b32 v78, s33, 0, v14
	v_mov_b32_e32 v14, v1
	v_mov_b32_e32 v15, v1
	v_cmp_lt_i32_e32 vcc, v17, v18
	v_bfi_b32 v66, s33, 0, v0
	v_bfi_b32 v79, s33, 0, v13
	v_bfi_b32 v77, s33, 0, v11
	v_bfi_b32 v76, s33, 0, v12
	v_bfi_b32 v75, s33, 0, v9
	v_bfi_b32 v74, s33, 0, v10
	v_bfi_b32 v73, s33, 0, v7
	v_bfi_b32 v72, s33, 0, v8
	v_bfi_b32 v71, s33, 0, v5
	v_bfi_b32 v70, s33, 0, v6
	v_bfi_b32 v69, s33, 0, v3
	v_bfi_b32 v68, s33, 0, v4
	v_bfi_b32 v67, s33, 0, v2
	v_mov_b32_e32 v0, v1
	v_mov_b32_e32 v2, v1
	v_mov_b32_e32 v3, v1
	v_mov_b32_e32 v4, v1
	v_mov_b32_e32 v5, v1
	v_mov_b32_e32 v6, v1
	v_mov_b32_e32 v7, v1
	v_mov_b32_e32 v8, v1
	v_mov_b32_e32 v9, v1
	v_mov_b32_e32 v10, v1
	v_mov_b32_e32 v11, v1
	v_mov_b32_e32 v12, v1
	v_mov_b32_e32 v13, v1
	v_cndmask_b32_e32 v17, v190, v17, vcc
	v_mov_b64_e32 v[64:65], v[14:15]
	v_mov_b64_e32 v[48:49], v[14:15]
	v_mov_b64_e32 v[32:33], v[14:15]
	v_lshlrev_b32_e32 v202, 2, v17
	v_add_u32_e32 v207, v16, v198
	v_mov_b64_e32 v[62:63], v[12:13]
	v_mov_b64_e32 v[60:61], v[10:11]
	v_mov_b64_e32 v[58:59], v[8:9]
	v_mov_b64_e32 v[56:57], v[6:7]
	v_mov_b64_e32 v[54:55], v[4:5]
	v_mov_b64_e32 v[52:53], v[2:3]
	v_mov_b64_e32 v[50:51], v[0:1]
	v_mov_b64_e32 v[46:47], v[12:13]
	v_mov_b64_e32 v[44:45], v[10:11]
	v_mov_b64_e32 v[42:43], v[8:9]
	v_mov_b64_e32 v[40:41], v[6:7]
	v_mov_b64_e32 v[38:39], v[4:5]
	v_mov_b64_e32 v[36:37], v[2:3]
	v_mov_b64_e32 v[34:35], v[0:1]
	v_mov_b64_e32 v[30:31], v[12:13]
	v_mov_b64_e32 v[28:29], v[10:11]
	v_mov_b64_e32 v[26:27], v[8:9]
	v_mov_b64_e32 v[24:25], v[6:7]
	v_mov_b64_e32 v[22:23], v[4:5]
	v_mov_b64_e32 v[20:21], v[2:3]
	v_mov_b64_e32 v[18:19], v[0:1]
	v_mov_b64_e32 v[16:17], v[14:15]
	v_add_u32_e32 v205, 0x8400, v204
	v_mov_b64_e32 v[14:15], v[12:13]
	v_mov_b64_e32 v[12:13], v[10:11]
	v_mov_b64_e32 v[10:11], v[8:9]
	v_mov_b64_e32 v[8:9], v[6:7]
	v_mov_b64_e32 v[6:7], v[4:5]
	v_mov_b64_e32 v[4:5], v[2:3]
	v_mov_b64_e32 v[2:3], v[0:1]
	s_mov_b32 s15, 0
	s_branch .LBB0_253
